# GEMM accumulator clears as 64 v_mov_b64 of 0 (was 128 v_mov_b32); dropped pads behind rewritten packed multiplies
# baseline (speedup 1.0000x reference)
.LBB0_214:
	s_ashr_i32 s19, s18, 31
	s_lshl_b64 s[20:21], s[18:19], 19
	s_add_u32 s20, s62, s20
	s_addc_u32 s21, s63, s21
	s_and_b64 s[34:35], s[2:3], exec
	s_cselect_b32 s19, s21, s55
	s_cselect_b32 s86, s20, s54
	s_ashr_i32 s15, s14, 31
	s_lshl_b64 s[34:35], s[14:15], 19
	s_add_u32 s34, s26, s34
	s_addc_u32 s35, s27, s35
	s_and_b64 s[60:61], s[2:3], exec
	s_cselect_b32 s15, s35, s59
	s_cselect_b32 s87, s34, s58
	s_add_u32 s54, s54, 0x40080
	s_addc_u32 s55, s55, 0
	s_add_u32 s88, s58, 0x100
	s_addc_u32 s89, s59, 0
	s_mov_b32 s90, -2
	v_mov_b64_e32 v[0:1], 0
	v_mov_b64_e32 v[2:3], 0
	v_mov_b64_e32 v[4:5], 0
	v_mov_b64_e32 v[6:7], 0
	v_mov_b64_e32 v[8:9], 0
	v_mov_b64_e32 v[10:11], 0
	v_mov_b64_e32 v[12:13], 0
	v_mov_b64_e32 v[14:15], 0
	v_mov_b64_e32 v[16:17], 0
	v_mov_b64_e32 v[18:19], 0
	v_mov_b64_e32 v[20:21], 0
	v_mov_b64_e32 v[22:23], 0
	v_mov_b64_e32 v[24:25], 0
	v_mov_b64_e32 v[26:27], 0
	v_mov_b64_e32 v[28:29], 0
	v_mov_b64_e32 v[30:31], 0
	v_mov_b64_e32 v[32:33], 0
	v_mov_b64_e32 v[34:35], 0
	v_mov_b64_e32 v[36:37], 0
	v_mov_b64_e32 v[38:39], 0
	v_mov_b64_e32 v[40:41], 0
	v_mov_b64_e32 v[42:43], 0
	v_mov_b64_e32 v[44:45], 0
	v_mov_b64_e32 v[46:47], 0
	v_mov_b64_e32 v[48:49], 0
	v_mov_b64_e32 v[50:51], 0
	v_mov_b64_e32 v[52:53], 0
	v_mov_b64_e32 v[54:55], 0
	v_mov_b64_e32 v[56:57], 0
	v_mov_b64_e32 v[58:59], 0
	v_mov_b64_e32 v[60:61], 0
	v_mov_b64_e32 v[62:63], 0
	v_mov_b64_e32 v[64:65], 0
	v_mov_b64_e32 v[66:67], 0
	v_mov_b64_e32 v[68:69], 0
	v_mov_b64_e32 v[70:71], 0
	v_mov_b64_e32 v[72:73], 0
	v_mov_b64_e32 v[74:75], 0
	v_mov_b64_e32 v[76:77], 0
	v_mov_b64_e32 v[78:79], 0
	v_mov_b64_e32 v[80:81], 0
	v_mov_b64_e32 v[82:83], 0
	v_mov_b64_e32 v[84:85], 0
	v_mov_b64_e32 v[86:87], 0
	v_mov_b64_e32 v[88:89], 0
	v_mov_b64_e32 v[90:91], 0
	v_mov_b64_e32 v[92:93], 0
	v_mov_b64_e32 v[94:95], 0
	v_mov_b64_e32 v[96:97], 0
	v_mov_b64_e32 v[98:99], 0
	v_mov_b64_e32 v[100:101], 0
	v_mov_b64_e32 v[102:103], 0
	v_mov_b64_e32 v[104:105], 0
	v_mov_b64_e32 v[106:107], 0
	v_mov_b64_e32 v[108:109], 0
	v_mov_b64_e32 v[110:111], 0
	v_mov_b64_e32 v[112:113], 0
	v_mov_b64_e32 v[114:115], 0
	v_mov_b64_e32 v[116:117], 0
	v_mov_b64_e32 v[118:119], 0
	v_mov_b64_e32 v[120:121], 0
	v_mov_b64_e32 v[122:123], 0
	v_mov_b64_e32 v[124:125], 0
	v_mov_b64_e32 v[126:127], 0

.LBB0_337:
	s_ashr_i32 s55, s54, 31
	s_lshl_b64 s[60:61], s[54:55], 20
	s_add_u32 s60, s4, s60
	s_addc_u32 s61, s5, s61
	s_and_b64 s[68:69], s[68:69], exec
	s_cselect_b32 s17, s61, s67
	s_cselect_b32 s55, s60, s66
	s_add_u32 s90, s66, 0x100
	s_addc_u32 s91, s67, 0
	s_add_u32 s62, s62, 0x600c00
	s_addc_u32 s63, s63, 0
	s_mov_b32 s93, -2
	v_mov_b64_e32 v[0:1], 0
	v_mov_b64_e32 v[2:3], 0
	v_mov_b64_e32 v[4:5], 0
	v_mov_b64_e32 v[6:7], 0
	v_mov_b64_e32 v[8:9], 0
	v_mov_b64_e32 v[10:11], 0
	v_mov_b64_e32 v[12:13], 0
	v_mov_b64_e32 v[14:15], 0
	v_mov_b64_e32 v[16:17], 0
	v_mov_b64_e32 v[18:19], 0
	v_mov_b64_e32 v[20:21], 0
	v_mov_b64_e32 v[22:23], 0
	v_mov_b64_e32 v[24:25], 0
	v_mov_b64_e32 v[26:27], 0
	v_mov_b64_e32 v[28:29], 0
	v_mov_b64_e32 v[30:31], 0
	v_mov_b64_e32 v[32:33], 0
	v_mov_b64_e32 v[34:35], 0
	v_mov_b64_e32 v[36:37], 0
	v_mov_b64_e32 v[38:39], 0
	v_mov_b64_e32 v[40:41], 0
	v_mov_b64_e32 v[42:43], 0
	v_mov_b64_e32 v[44:45], 0
	v_mov_b64_e32 v[46:47], 0
	v_mov_b64_e32 v[48:49], 0
	v_mov_b64_e32 v[50:51], 0
	v_mov_b64_e32 v[52:53], 0
	v_mov_b64_e32 v[54:55], 0
	v_mov_b64_e32 v[56:57], 0
	v_mov_b64_e32 v[58:59], 0
	v_mov_b64_e32 v[60:61], 0
	v_mov_b64_e32 v[62:63], 0
	v_mov_b64_e32 v[64:65], 0
	v_mov_b64_e32 v[66:67], 0
	v_mov_b64_e32 v[68:69], 0
	v_mov_b64_e32 v[70:71], 0
	v_mov_b64_e32 v[72:73], 0
	v_mov_b64_e32 v[74:75], 0
	v_mov_b64_e32 v[76:77], 0
	v_mov_b64_e32 v[78:79], 0
	v_mov_b64_e32 v[80:81], 0
	v_mov_b64_e32 v[82:83], 0
	v_mov_b64_e32 v[84:85], 0
	v_mov_b64_e32 v[86:87], 0
	v_mov_b64_e32 v[88:89], 0
	v_mov_b64_e32 v[90:91], 0
	v_mov_b64_e32 v[92:93], 0
	v_mov_b64_e32 v[94:95], 0
	v_mov_b64_e32 v[96:97], 0
	v_mov_b64_e32 v[98:99], 0
	v_mov_b64_e32 v[100:101], 0
	v_mov_b64_e32 v[102:103], 0
	v_mov_b64_e32 v[104:105], 0
	v_mov_b64_e32 v[106:107], 0
	v_mov_b64_e32 v[108:109], 0
	v_mov_b64_e32 v[110:111], 0
	v_mov_b64_e32 v[112:113], 0
	v_mov_b64_e32 v[114:115], 0
	v_mov_b64_e32 v[116:117], 0
	v_mov_b64_e32 v[118:119], 0
	v_mov_b64_e32 v[120:121], 0
	v_mov_b64_e32 v[122:123], 0
	v_mov_b64_e32 v[124:125], 0
	v_mov_b64_e32 v[126:127], 0
	s_branch .LBB0_339

.LBB0_361:
	s_ashr_i32 s55, s54, 31
	s_lshl_b64 s[60:61], s[54:55], 20
	s_add_u32 s60, s4, s60
	s_addc_u32 s61, s5, s61
	s_and_b64 s[68:69], s[68:69], exec
	s_cselect_b32 s17, s61, s67
	s_cselect_b32 s55, s60, s66
	s_add_u32 s90, s66, 0x100
	s_addc_u32 s91, s67, 0
	s_add_u32 s62, s62, 0x600c00
	s_addc_u32 s63, s63, 0
	s_mov_b32 s94, -2
	v_mov_b64_e32 v[0:1], 0
	v_mov_b64_e32 v[2:3], 0
	v_mov_b64_e32 v[4:5], 0
	v_mov_b64_e32 v[6:7], 0
	v_mov_b64_e32 v[8:9], 0
	v_mov_b64_e32 v[10:11], 0
	v_mov_b64_e32 v[12:13], 0
	v_mov_b64_e32 v[14:15], 0
	v_mov_b64_e32 v[16:17], 0
	v_mov_b64_e32 v[18:19], 0
	v_mov_b64_e32 v[20:21], 0
	v_mov_b64_e32 v[22:23], 0
	v_mov_b64_e32 v[24:25], 0
	v_mov_b64_e32 v[26:27], 0
	v_mov_b64_e32 v[28:29], 0
	v_mov_b64_e32 v[30:31], 0
	v_mov_b64_e32 v[32:33], 0
	v_mov_b64_e32 v[34:35], 0
	v_mov_b64_e32 v[36:37], 0
	v_mov_b64_e32 v[38:39], 0
	v_mov_b64_e32 v[40:41], 0
	v_mov_b64_e32 v[42:43], 0
	v_mov_b64_e32 v[44:45], 0
	v_mov_b64_e32 v[46:47], 0
	v_mov_b64_e32 v[48:49], 0
	v_mov_b64_e32 v[50:51], 0
	v_mov_b64_e32 v[52:53], 0
	v_mov_b64_e32 v[54:55], 0
	v_mov_b64_e32 v[56:57], 0
	v_mov_b64_e32 v[58:59], 0
	v_mov_b64_e32 v[60:61], 0
	v_mov_b64_e32 v[62:63], 0
	v_mov_b64_e32 v[64:65], 0
	v_mov_b64_e32 v[66:67], 0
	v_mov_b64_e32 v[68:69], 0
	v_mov_b64_e32 v[70:71], 0
	v_mov_b64_e32 v[72:73], 0
	v_mov_b64_e32 v[74:75], 0
	v_mov_b64_e32 v[76:77], 0
	v_mov_b64_e32 v[78:79], 0
	v_mov_b64_e32 v[80:81], 0
	v_mov_b64_e32 v[82:83], 0
	v_mov_b64_e32 v[84:85], 0
	v_mov_b64_e32 v[86:87], 0
	v_mov_b64_e32 v[88:89], 0
	v_mov_b64_e32 v[90:91], 0
	v_mov_b64_e32 v[92:93], 0
	v_mov_b64_e32 v[94:95], 0
	v_mov_b64_e32 v[96:97], 0
	v_mov_b64_e32 v[98:99], 0
	v_mov_b64_e32 v[100:101], 0
	v_mov_b64_e32 v[102:103], 0
	v_mov_b64_e32 v[104:105], 0
	v_mov_b64_e32 v[106:107], 0
	v_mov_b64_e32 v[108:109], 0
	v_mov_b64_e32 v[110:111], 0
	v_mov_b64_e32 v[112:113], 0
	v_mov_b64_e32 v[114:115], 0
	v_mov_b64_e32 v[116:117], 0
	v_mov_b64_e32 v[118:119], 0
	v_mov_b64_e32 v[120:121], 0
	v_mov_b64_e32 v[122:123], 0
	v_mov_b64_e32 v[124:125], 0
	v_mov_b64_e32 v[126:127], 0
	s_branch .LBB0_363

.LBB0_383:
	s_ashr_i32 s45, s44, 31
	s_lshl_b64 s[50:51], s[44:45], 19
	s_add_u32 s50, s67, s50
	s_addc_u32 s51, s68, s51
	s_and_b64 s[54:55], s[2:3], exec
	s_cselect_b32 s17, s51, s59
	s_cselect_b32 s45, s50, s58
	s_ashr_i32 s35, s34, 31
	s_lshl_b64 s[54:55], s[34:35], 19
	s_add_u32 s54, s69, s54
	s_addc_u32 s55, s72, s55
	s_and_b64 s[62:63], s[2:3], exec
	s_cselect_b32 s35, s55, s61
	s_cselect_b32 s89, s54, s60
	s_add_u32 s58, s58, 0x40080
	s_addc_u32 s59, s59, 0
	s_add_u32 s90, s60, 0x100
	s_addc_u32 s91, s61, 0
	s_mov_b32 s92, -2
	v_mov_b64_e32 v[0:1], 0
	v_mov_b64_e32 v[2:3], 0
	v_mov_b64_e32 v[4:5], 0
	v_mov_b64_e32 v[6:7], 0
	v_mov_b64_e32 v[8:9], 0
	v_mov_b64_e32 v[10:11], 0
	v_mov_b64_e32 v[12:13], 0
	v_mov_b64_e32 v[14:15], 0
	v_mov_b64_e32 v[16:17], 0
	v_mov_b64_e32 v[18:19], 0
	v_mov_b64_e32 v[20:21], 0
	v_mov_b64_e32 v[22:23], 0
	v_mov_b64_e32 v[24:25], 0
	v_mov_b64_e32 v[26:27], 0
	v_mov_b64_e32 v[28:29], 0
	v_mov_b64_e32 v[30:31], 0
	v_mov_b64_e32 v[32:33], 0
	v_mov_b64_e32 v[34:35], 0
	v_mov_b64_e32 v[36:37], 0
	v_mov_b64_e32 v[38:39], 0
	v_mov_b64_e32 v[40:41], 0
	v_mov_b64_e32 v[42:43], 0
	v_mov_b64_e32 v[44:45], 0
	v_mov_b64_e32 v[46:47], 0
	v_mov_b64_e32 v[48:49], 0
	v_mov_b64_e32 v[50:51], 0
	v_mov_b64_e32 v[52:53], 0
	v_mov_b64_e32 v[54:55], 0
	v_mov_b64_e32 v[56:57], 0
	v_mov_b64_e32 v[58:59], 0
	v_mov_b64_e32 v[60:61], 0
	v_mov_b64_e32 v[62:63], 0
	v_mov_b64_e32 v[64:65], 0
	v_mov_b64_e32 v[66:67], 0
	v_mov_b64_e32 v[68:69], 0
	v_mov_b64_e32 v[70:71], 0
	v_mov_b64_e32 v[72:73], 0
	v_mov_b64_e32 v[74:75], 0
	v_mov_b64_e32 v[76:77], 0
	v_mov_b64_e32 v[78:79], 0
	v_mov_b64_e32 v[80:81], 0
	v_mov_b64_e32 v[82:83], 0
	v_mov_b64_e32 v[84:85], 0
	v_mov_b64_e32 v[86:87], 0
	v_mov_b64_e32 v[88:89], 0
	v_mov_b64_e32 v[90:91], 0
	v_mov_b64_e32 v[92:93], 0
	v_mov_b64_e32 v[94:95], 0
	v_mov_b64_e32 v[96:97], 0
	v_mov_b64_e32 v[98:99], 0
	v_mov_b64_e32 v[100:101], 0
	v_mov_b64_e32 v[102:103], 0
	v_mov_b64_e32 v[104:105], 0
	v_mov_b64_e32 v[106:107], 0
	v_mov_b64_e32 v[108:109], 0
	v_mov_b64_e32 v[110:111], 0
	v_mov_b64_e32 v[112:113], 0
	v_mov_b64_e32 v[114:115], 0
	v_mov_b64_e32 v[116:117], 0
	v_mov_b64_e32 v[118:119], 0
	v_mov_b64_e32 v[120:121], 0
	v_mov_b64_e32 v[122:123], 0
	v_mov_b64_e32 v[124:125], 0
	v_mov_b64_e32 v[126:127], 0

.LBB0_728:
	s_ashr_i32 s45, s44, 31
	s_lshl_b64 s[50:51], s[44:45], 19
	s_add_u32 s50, s11, s50
	s_addc_u32 s51, s17, s51
	s_and_b64 s[54:55], s[2:3], exec
	s_cselect_b32 s45, s51, s59
	s_cselect_b32 s78, s50, s58
	s_ashr_i32 s35, s34, 31
	s_lshl_b64 s[54:55], s[34:35], 19
	s_add_u32 s54, s64, s54
	s_addc_u32 s55, s65, s55
	s_and_b64 s[62:63], s[2:3], exec
	s_cselect_b32 s35, s55, s61
	s_cselect_b32 s79, s54, s60
	s_add_u32 s58, s58, 0x40080
	s_addc_u32 s59, s59, 0
	s_add_u32 s80, s60, 0x100
	s_addc_u32 s81, s61, 0
	s_mov_b32 s82, -2
	v_mov_b64_e32 v[0:1], 0
	v_mov_b64_e32 v[2:3], 0
	v_mov_b64_e32 v[4:5], 0
	v_mov_b64_e32 v[6:7], 0
	v_mov_b64_e32 v[8:9], 0
	v_mov_b64_e32 v[10:11], 0
	v_mov_b64_e32 v[12:13], 0
	v_mov_b64_e32 v[14:15], 0
	v_mov_b64_e32 v[16:17], 0
	v_mov_b64_e32 v[18:19], 0
	v_mov_b64_e32 v[20:21], 0
	v_mov_b64_e32 v[22:23], 0
	v_mov_b64_e32 v[24:25], 0
	v_mov_b64_e32 v[26:27], 0
	v_mov_b64_e32 v[28:29], 0
	v_mov_b64_e32 v[30:31], 0
	v_mov_b64_e32 v[32:33], 0
	v_mov_b64_e32 v[34:35], 0
	v_mov_b64_e32 v[36:37], 0
	v_mov_b64_e32 v[38:39], 0
	v_mov_b64_e32 v[40:41], 0
	v_mov_b64_e32 v[42:43], 0
	v_mov_b64_e32 v[44:45], 0
	v_mov_b64_e32 v[46:47], 0
	v_mov_b64_e32 v[48:49], 0
	v_mov_b64_e32 v[50:51], 0
	v_mov_b64_e32 v[52:53], 0
	v_mov_b64_e32 v[54:55], 0
	v_mov_b64_e32 v[56:57], 0
	v_mov_b64_e32 v[58:59], 0
	v_mov_b64_e32 v[60:61], 0
	v_mov_b64_e32 v[62:63], 0
	v_mov_b64_e32 v[64:65], 0
	v_mov_b64_e32 v[66:67], 0
	v_mov_b64_e32 v[68:69], 0
	v_mov_b64_e32 v[70:71], 0
	v_mov_b64_e32 v[72:73], 0
	v_mov_b64_e32 v[74:75], 0
	v_mov_b64_e32 v[76:77], 0
	v_mov_b64_e32 v[78:79], 0
	v_mov_b64_e32 v[80:81], 0
	v_mov_b64_e32 v[82:83], 0
	v_mov_b64_e32 v[84:85], 0
	v_mov_b64_e32 v[86:87], 0
	v_mov_b64_e32 v[88:89], 0
	v_mov_b64_e32 v[90:91], 0
	v_mov_b64_e32 v[92:93], 0
	v_mov_b64_e32 v[94:95], 0
	v_mov_b64_e32 v[96:97], 0
	v_mov_b64_e32 v[98:99], 0
	v_mov_b64_e32 v[100:101], 0
	v_mov_b64_e32 v[102:103], 0
	v_mov_b64_e32 v[104:105], 0
	v_mov_b64_e32 v[106:107], 0
	v_mov_b64_e32 v[108:109], 0
	v_mov_b64_e32 v[110:111], 0
	v_mov_b64_e32 v[112:113], 0
	v_mov_b64_e32 v[114:115], 0
	v_mov_b64_e32 v[116:117], 0
	v_mov_b64_e32 v[118:119], 0
	v_mov_b64_e32 v[120:121], 0
	v_mov_b64_e32 v[122:123], 0
	v_mov_b64_e32 v[124:125], 0
	v_mov_b64_e32 v[126:127], 0

.LBB0_865:
	s_ashr_i32 s55, s54, 31
	s_lshl_b64 s[58:59], s[54:55], 19
	s_add_u32 s58, s17, s58
	s_addc_u32 s59, s68, s59
	s_and_b64 s[60:61], s[6:7], exec
	s_cselect_b32 s55, s59, s63
	s_cselect_b32 s86, s58, s62
	s_ashr_i32 s53, s52, 31
	s_lshl_b64 s[60:61], s[52:53], 19
	s_add_u32 s60, s69, s60
	s_addc_u32 s61, s70, s61
	s_and_b64 s[66:67], s[6:7], exec
	s_cselect_b32 s53, s61, s65
	s_cselect_b32 s87, s60, s64
	s_add_u32 s62, s62, 0x40080
	s_addc_u32 s63, s63, 0
	s_add_u32 s88, s64, 0x100
	s_addc_u32 s89, s65, 0
	s_mov_b32 s90, -2
	v_mov_b64_e32 v[0:1], 0
	v_mov_b64_e32 v[2:3], 0
	v_mov_b64_e32 v[4:5], 0
	v_mov_b64_e32 v[6:7], 0
	v_mov_b64_e32 v[8:9], 0
	v_mov_b64_e32 v[10:11], 0
	v_mov_b64_e32 v[12:13], 0
	v_mov_b64_e32 v[14:15], 0
	v_mov_b64_e32 v[16:17], 0
	v_mov_b64_e32 v[18:19], 0
	v_mov_b64_e32 v[20:21], 0
	v_mov_b64_e32 v[22:23], 0
	v_mov_b64_e32 v[24:25], 0
	v_mov_b64_e32 v[26:27], 0
	v_mov_b64_e32 v[28:29], 0
	v_mov_b64_e32 v[30:31], 0
	v_mov_b64_e32 v[32:33], 0
	v_mov_b64_e32 v[34:35], 0
	v_mov_b64_e32 v[36:37], 0
	v_mov_b64_e32 v[38:39], 0
	v_mov_b64_e32 v[40:41], 0
	v_mov_b64_e32 v[42:43], 0
	v_mov_b64_e32 v[44:45], 0
	v_mov_b64_e32 v[46:47], 0
	v_mov_b64_e32 v[48:49], 0
	v_mov_b64_e32 v[50:51], 0
	v_mov_b64_e32 v[52:53], 0
	v_mov_b64_e32 v[54:55], 0
	v_mov_b64_e32 v[56:57], 0
	v_mov_b64_e32 v[58:59], 0
	v_mov_b64_e32 v[60:61], 0
	v_mov_b64_e32 v[62:63], 0
	v_mov_b64_e32 v[96:97], 0
	v_mov_b64_e32 v[98:99], 0
	v_mov_b64_e32 v[100:101], 0
	v_mov_b64_e32 v[102:103], 0
	v_mov_b64_e32 v[104:105], 0
	v_mov_b64_e32 v[106:107], 0
	v_mov_b64_e32 v[108:109], 0
	v_mov_b64_e32 v[110:111], 0
	v_mov_b64_e32 v[112:113], 0
	v_mov_b64_e32 v[114:115], 0
	v_mov_b64_e32 v[116:117], 0
	v_mov_b64_e32 v[118:119], 0
	v_mov_b64_e32 v[120:121], 0
	v_mov_b64_e32 v[122:123], 0
	v_mov_b64_e32 v[124:125], 0
	v_mov_b64_e32 v[126:127], 0
	v_mov_b64_e32 v[128:129], 0
	v_mov_b64_e32 v[130:131], 0
	v_mov_b64_e32 v[132:133], 0
	v_mov_b64_e32 v[134:135], 0
	v_mov_b64_e32 v[136:137], 0
	v_mov_b64_e32 v[138:139], 0
	v_mov_b64_e32 v[140:141], 0
	v_mov_b64_e32 v[142:143], 0
	v_mov_b64_e32 v[144:145], 0
	v_mov_b64_e32 v[146:147], 0
	v_mov_b64_e32 v[148:149], 0
	v_mov_b64_e32 v[150:151], 0
	v_mov_b64_e32 v[152:153], 0
	v_mov_b64_e32 v[154:155], 0
	v_mov_b64_e32 v[156:157], 0
	v_mov_b64_e32 v[158:159], 0

.LBB0_871:
	s_or_saveexec_b64 s[66:67], s[66:67]
	v_lshl_add_u32 v208, s0, 8, v169
	s_xor_b64 exec, exec, s[66:67]
	s_cbranch_execz .LBB0_873
	v_mov_b32_e32 v214, v147
	s_waitcnt vmcnt(0)
	v_mov_b32_e32 v215, v95
	v_mov_b32_e32 v198, v91
	v_pk_mul_f32 v[198:199], v[214:215], v[198:199]
	s_nop 0
	v_fma_f32 v182, v83, v196, v199
	v_add_f32_e32 v182, v198, v182
	v_add_f32_e32 v182, v87, v182
	v_mov_b32_e32 v198, v146
	v_mov_b32_e32 v199, v94
	v_mov_b32_e32 v196, v90
	v_mul_f32_e32 v184, v182, v182
	v_pk_mul_f32 v[196:197], v[198:199], v[196:197]
	v_fmamk_f32 v184, v184, 0xbdd2d3e8, v206
	v_fma_f32 v186, v82, v194, v197
	v_mul_f32_e32 v184, v182, v184
	v_add_f32_e32 v186, v196, v186
	v_exp_f32_e32 v184, v184
	v_add_f32_e32 v186, v86, v186
	v_mul_f32_e32 v188, v186, v186
	v_fmamk_f32 v188, v188, 0xbdd2d3e8, v206
	v_mul_f32_e32 v188, v186, v188
	v_exp_f32_e32 v188, v188
	v_add_f32_e32 v184, 1.0, v184
	v_rcp_f32_e32 v184, v184
	v_mov_b32_e32 v196, v145
	v_add_f32_e32 v188, 1.0, v188
	v_mov_b32_e32 v197, v93
	v_mov_b32_e32 v194, v89
	v_rcp_f32_e32 v188, v188
	v_mul_f32_e32 v182, v182, v184
	v_pk_mul_f32 v[194:195], v[196:197], v[194:195]
	v_mul_f32_e32 v198, v159, v182
	v_fma_f32 v182, v81, v192, v195
	v_add_f32_e32 v182, v194, v182
	v_mov_b32_e32 v194, v144
	v_mov_b32_e32 v195, v92
	v_mov_b32_e32 v192, v88
	v_pk_mul_f32 v[192:193], v[194:195], v[192:193]
	v_mul_f32_e32 v159, v186, v188
	v_fma_f32 v186, v80, v213, v193
	v_add_f32_e32 v182, v85, v182
	v_add_f32_e32 v186, v192, v186
	v_mul_f32_e32 v184, v182, v182
	v_add_f32_e32 v186, v84, v186
	v_fmamk_f32 v184, v184, 0xbdd2d3e8, v206
	v_mul_f32_e32 v188, v186, v186
	v_mul_f32_e32 v184, v182, v184
	v_fmamk_f32 v188, v188, 0xbdd2d3e8, v206
	v_exp_f32_e32 v184, v184
	v_mul_f32_e32 v188, v186, v188
	v_exp_f32_e32 v188, v188
	v_mul_f32_e32 v192, v158, v159
	v_add_f32_e32 v158, 1.0, v184
	v_rcp_f32_e32 v184, v158
	v_add_f32_e32 v158, 1.0, v188
	v_rcp_f32_e32 v193, v158
	v_fma_f32 v158, v75, v151, v71
	v_fmac_f32_e32 v158, v79, v189
	v_fma_f32 v188, v67, v212, v158
	v_mul_f32_e32 v158, v188, v188
	v_fmamk_f32 v158, v158, 0xbdd2d3e8, v206
	v_mul_f32_e32 v158, v188, v158
	v_exp_f32_e32 v158, v158
	v_mul_f32_e32 v159, v182, v184
	v_mul_f32_e32 v189, v157, v159
	v_mul_f32_e32 v157, v186, v193
	v_add_f32_e32 v158, 1.0, v158
	v_rcp_f32_e32 v182, v158
	v_fma_f32 v158, v74, v150, v70
	v_fmac_f32_e32 v158, v78, v187
	v_mul_f32_e32 v186, v156, v157
	v_fma_f32 v158, v66, v211, v158
	v_mul_f32_e32 v159, v158, v158
	v_fmamk_f32 v159, v159, 0xbdd2d3e8, v206
	v_mul_f32_e32 v159, v158, v159
	v_exp_f32_e32 v159, v159
	v_mul_f32_e32 v156, v188, v182
	v_mul_f32_e32 v155, v155, v156
	v_add_f32_e32 v156, 1.0, v159
	v_rcp_f32_e32 v159, v156
	v_fma_f32 v156, v73, v149, v69
	v_fmac_f32_e32 v156, v77, v185
	v_fma_f32 v184, v65, v210, v156
	v_mul_f32_e32 v156, v184, v184
	v_fmamk_f32 v156, v156, 0xbdd2d3e8, v206
	v_mul_f32_e32 v156, v184, v156
	v_exp_f32_e32 v185, v156
	v_fma_f32 v156, v72, v148, v68
	v_fmac_f32_e32 v156, v76, v183
	v_mul_f32_e32 v158, v158, v159
	v_fma_f32 v156, v64, v209, v156
	v_mul_f32_e32 v157, v156, v156
	v_fmamk_f32 v157, v157, 0xbdd2d3e8, v206
	v_mul_f32_e32 v157, v156, v157
	v_exp_f32_e32 v157, v157
	v_add_f32_e32 v159, 1.0, v185
	v_rcp_f32_e32 v159, v159
	v_mul_f32_e32 v154, v154, v158
	v_add_f32_e32 v157, 1.0, v157
	v_rcp_f32_e32 v157, v157
	v_mul_f32_e32 v158, v184, v159
	v_mul_f32_e32 v153, v153, v158
	v_mov_b32_e32 v182, v73
	v_mul_f32_e32 v156, v156, v157
	v_mul_f32_e32 v152, v152, v156
	v_mov_b64_e32 v[156:157], s[10:11]
	v_mad_i64_i32 v[156:157], s[0:1], v208, s85, v[156:157]
	v_cvt_pk_bf16_f32 v152, v152, v153
	v_cvt_pk_bf16_f32 v153, v154, v155
	v_cvt_pk_bf16_f32 v154, v186, v189
	v_lshl_add_u64 v[156:157], v[180:181], 1, v[156:157]
	v_mov_b32_e32 v184, v75
	v_mov_b32_e32 v186, v89
	v_mov_b32_e32 v188, v91
	v_cvt_pk_bf16_f32 v155, v192, v198
	global_store_dwordx4 v[156:157], v[152:155], off

.LBB0_877:
	s_andn2_saveexec_b64 s[64:65], s[64:65]
	s_cbranch_execz .LBB0_879
	v_fma_f32 v104, v188, v51, v87
	v_fmac_f32_e32 v104, v95, v189
	v_fma_f32 v103, v83, v103, v104
	v_mul_f32_e32 v104, v103, v103
	v_fmamk_f32 v104, v104, 0xbdd2d3e8, v206
	v_mul_f32_e32 v104, v103, v104
	v_exp_f32_e32 v106, v104
	v_fma_f32 v104, v90, v50, v86
	v_fmac_f32_e32 v104, v94, v91
	v_fma_f32 v91, v82, v102, v104
	v_mul_f32_e32 v102, v91, v91
	v_fmamk_f32 v102, v102, 0xbdd2d3e8, v206
	v_mul_f32_e32 v102, v91, v102
	v_exp_f32_e32 v102, v102
	v_add_f32_e32 v104, 1.0, v106
	v_rcp_f32_e32 v104, v104
	v_add_f32_e32 v102, 1.0, v102
	v_rcp_f32_e32 v102, v102
	v_mul_f32_e32 v103, v103, v104
	v_mul_f32_e32 v104, v63, v103
	v_mul_f32_e32 v63, v91, v102
	v_fma_f32 v102, v186, v49, v85
	v_fmac_f32_e32 v102, v93, v187
	v_fma_f32 v91, v81, v101, v102
	v_fma_f32 v102, v88, v48, v84
	v_fmac_f32_e32 v102, v92, v89
	v_fma_f32 v89, v80, v100, v102
	v_mul_f32_e32 v101, v91, v91
	v_fmamk_f32 v101, v101, 0xbdd2d3e8, v206
	v_mul_f32_e32 v100, v89, v89
	v_mul_f32_e32 v101, v91, v101
	v_fmamk_f32 v100, v100, 0xbdd2d3e8, v206
	v_exp_f32_e32 v101, v101
	v_mul_f32_e32 v100, v89, v100
	v_exp_f32_e32 v100, v100
	v_mul_f32_e32 v102, v62, v63
	v_add_f32_e32 v62, 1.0, v101
	v_rcp_f32_e32 v101, v62
	v_add_f32_e32 v62, 1.0, v100
	v_rcp_f32_e32 v100, v62
	v_fma_f32 v62, v184, v55, v71
	v_fmac_f32_e32 v62, v79, v185
	v_fma_f32 v99, v67, v99, v62
	v_mul_f32_e32 v62, v99, v99
	v_fmamk_f32 v62, v62, 0xbdd2d3e8, v206
	v_mul_f32_e32 v62, v99, v62
	v_exp_f32_e32 v62, v62
	v_mul_f32_e32 v63, v91, v101
	v_mul_f32_e32 v91, v61, v63
	v_mul_f32_e32 v61, v89, v100
	v_add_f32_e32 v62, 1.0, v62
	v_rcp_f32_e32 v89, v62
	v_fma_f32 v62, v74, v54, v70
	v_fmac_f32_e32 v62, v78, v75
	v_mul_f32_e32 v75, v60, v61
	v_fma_f32 v62, v66, v98, v62
	v_mul_f32_e32 v63, v62, v62
	v_fmamk_f32 v63, v63, 0xbdd2d3e8, v206
	v_mul_f32_e32 v63, v62, v63
	v_exp_f32_e32 v63, v63
	v_mul_f32_e32 v60, v99, v89
	v_mul_f32_e32 v59, v59, v60
	v_add_f32_e32 v60, 1.0, v63
	v_rcp_f32_e32 v63, v60
	v_fma_f32 v60, v182, v53, v69
	v_fmac_f32_e32 v60, v77, v183
	v_mul_f32_e32 v62, v62, v63
	v_fma_f32 v89, v65, v97, v60
	v_mul_f32_e32 v60, v89, v89
	v_fmamk_f32 v60, v60, 0xbdd2d3e8, v206
	v_mul_f32_e32 v60, v89, v60
	v_exp_f32_e32 v97, v60
	v_fma_f32 v60, v72, v52, v68
	v_fmac_f32_e32 v60, v76, v73
	v_add_f32_e32 v63, 1.0, v97
	v_fma_f32 v60, v64, v96, v60
	v_mul_f32_e32 v61, v60, v60
	v_fmamk_f32 v61, v61, 0xbdd2d3e8, v206
	v_mul_f32_e32 v61, v60, v61
	v_exp_f32_e32 v61, v61
	v_rcp_f32_e32 v63, v63
	v_mul_f32_e32 v58, v58, v62
	v_add_f32_e32 v61, 1.0, v61
	v_rcp_f32_e32 v61, v61
	v_mul_f32_e32 v62, v89, v63
	v_mul_f32_e32 v57, v57, v62
	v_add_u32_e32 v62, 0x80, v208
	v_mul_f32_e32 v60, v60, v61
	v_mul_f32_e32 v56, v56, v60
	v_mov_b64_e32 v[60:61], s[10:11]
	v_mad_i64_i32 v[60:61], s[0:1], v62, s85, v[60:61]
	v_lshl_add_u64 v[60:61], v[180:181], 1, v[60:61]
	v_cvt_pk_bf16_f32 v56, v56, v57
	v_cvt_pk_bf16_f32 v57, v58, v59
	v_cvt_pk_bf16_f32 v58, v75, v91
	v_cvt_pk_bf16_f32 v59, v102, v104
	global_store_dwordx4 v[60:61], v[56:59], off

.LBB0_1017:
	s_add_u32 s52, s52, 0xb0080
	s_addc_u32 s53, s53, 0
	s_add_u32 s76, s54, 0x100
	s_addc_u32 s77, s55, 0
	s_mov_b32 s78, -2
	v_mov_b64_e32 v[0:1], 0
	v_mov_b64_e32 v[2:3], 0
	v_mov_b64_e32 v[4:5], 0
	v_mov_b64_e32 v[6:7], 0
	v_mov_b64_e32 v[8:9], 0
	v_mov_b64_e32 v[10:11], 0
	v_mov_b64_e32 v[12:13], 0
	v_mov_b64_e32 v[14:15], 0
	v_mov_b64_e32 v[16:17], 0
	v_mov_b64_e32 v[18:19], 0
	v_mov_b64_e32 v[20:21], 0
	v_mov_b64_e32 v[22:23], 0
	v_mov_b64_e32 v[24:25], 0
	v_mov_b64_e32 v[26:27], 0
	v_mov_b64_e32 v[28:29], 0
	v_mov_b64_e32 v[30:31], 0
	v_mov_b64_e32 v[32:33], 0
	v_mov_b64_e32 v[34:35], 0
	v_mov_b64_e32 v[36:37], 0
	v_mov_b64_e32 v[38:39], 0
	v_mov_b64_e32 v[40:41], 0
	v_mov_b64_e32 v[42:43], 0
	v_mov_b64_e32 v[44:45], 0
	v_mov_b64_e32 v[46:47], 0
	v_mov_b64_e32 v[48:49], 0
	v_mov_b64_e32 v[50:51], 0
	v_mov_b64_e32 v[52:53], 0
	v_mov_b64_e32 v[54:55], 0
	v_mov_b64_e32 v[56:57], 0
	v_mov_b64_e32 v[58:59], 0
	v_mov_b64_e32 v[60:61], 0
	v_mov_b64_e32 v[62:63], 0
	v_mov_b64_e32 v[64:65], 0
	v_mov_b64_e32 v[66:67], 0
	v_mov_b64_e32 v[68:69], 0
	v_mov_b64_e32 v[70:71], 0
	v_mov_b64_e32 v[72:73], 0
	v_mov_b64_e32 v[74:75], 0
	v_mov_b64_e32 v[76:77], 0
	v_mov_b64_e32 v[78:79], 0
	v_mov_b64_e32 v[80:81], 0
	v_mov_b64_e32 v[82:83], 0
	v_mov_b64_e32 v[84:85], 0
	v_mov_b64_e32 v[86:87], 0
	v_mov_b64_e32 v[88:89], 0
	v_mov_b64_e32 v[90:91], 0
	v_mov_b64_e32 v[92:93], 0
	v_mov_b64_e32 v[94:95], 0
	v_mov_b64_e32 v[96:97], 0
	v_mov_b64_e32 v[98:99], 0
	v_mov_b64_e32 v[100:101], 0
	v_mov_b64_e32 v[102:103], 0
	v_mov_b64_e32 v[104:105], 0
	v_mov_b64_e32 v[106:107], 0
	v_mov_b64_e32 v[108:109], 0
	v_mov_b64_e32 v[110:111], 0
	v_mov_b64_e32 v[112:113], 0
	v_mov_b64_e32 v[114:115], 0
	v_mov_b64_e32 v[116:117], 0
	v_mov_b64_e32 v[118:119], 0
	v_mov_b64_e32 v[120:121], 0
	v_mov_b64_e32 v[122:123], 0
	v_mov_b64_e32 v[124:125], 0
	v_mov_b64_e32 v[126:127], 0

.LBB0_1154:
	s_ashr_i32 s15, s14, 31
	s_lshl_b64 s[18:19], s[14:15], 19
	s_add_u32 s18, s17, s18
	s_addc_u32 s19, s52, s19
	s_and_b64 s[20:21], s[2:3], exec
	s_cselect_b32 s15, s19, s35
	s_cselect_b32 s70, s18, s34
	s_ashr_i32 s13, s12, 31
	s_lshl_b64 s[20:21], s[12:13], 19
	s_add_u32 s20, s53, s20
	s_addc_u32 s21, s54, s21
	s_and_b64 s[50:51], s[2:3], exec
	s_cselect_b32 s13, s21, s45
	s_cselect_b32 s71, s20, s44
	s_add_u32 s34, s34, 0x40080
	s_addc_u32 s35, s35, 0
	s_add_u32 s72, s44, 0x100
	s_addc_u32 s73, s45, 0
	s_mov_b32 s74, -2
	v_mov_b64_e32 v[0:1], 0
	v_mov_b64_e32 v[2:3], 0
	v_mov_b64_e32 v[4:5], 0
	v_mov_b64_e32 v[6:7], 0
	v_mov_b64_e32 v[8:9], 0
	v_mov_b64_e32 v[10:11], 0
	v_mov_b64_e32 v[12:13], 0
	v_mov_b64_e32 v[14:15], 0
	v_mov_b64_e32 v[16:17], 0
	v_mov_b64_e32 v[18:19], 0
	v_mov_b64_e32 v[20:21], 0
	v_mov_b64_e32 v[22:23], 0
	v_mov_b64_e32 v[24:25], 0
	v_mov_b64_e32 v[26:27], 0
	v_mov_b64_e32 v[28:29], 0
	v_mov_b64_e32 v[30:31], 0
	v_mov_b64_e32 v[32:33], 0
	v_mov_b64_e32 v[34:35], 0
	v_mov_b64_e32 v[36:37], 0
	v_mov_b64_e32 v[38:39], 0
	v_mov_b64_e32 v[40:41], 0
	v_mov_b64_e32 v[42:43], 0
	v_mov_b64_e32 v[44:45], 0
	v_mov_b64_e32 v[46:47], 0
	v_mov_b64_e32 v[48:49], 0
	v_mov_b64_e32 v[50:51], 0
	v_mov_b64_e32 v[52:53], 0
	v_mov_b64_e32 v[54:55], 0
	v_mov_b64_e32 v[56:57], 0
	v_mov_b64_e32 v[58:59], 0
	v_mov_b64_e32 v[60:61], 0
	v_mov_b64_e32 v[62:63], 0
	v_mov_b64_e32 v[64:65], 0
	v_mov_b64_e32 v[66:67], 0
	v_mov_b64_e32 v[68:69], 0
	v_mov_b64_e32 v[70:71], 0
	v_mov_b64_e32 v[72:73], 0
	v_mov_b64_e32 v[74:75], 0
	v_mov_b64_e32 v[76:77], 0
	v_mov_b64_e32 v[78:79], 0
	v_mov_b64_e32 v[80:81], 0
	v_mov_b64_e32 v[82:83], 0
	v_mov_b64_e32 v[84:85], 0
	v_mov_b64_e32 v[86:87], 0
	v_mov_b64_e32 v[88:89], 0
	v_mov_b64_e32 v[90:91], 0
	v_mov_b64_e32 v[92:93], 0
	v_mov_b64_e32 v[94:95], 0
	v_mov_b64_e32 v[96:97], 0
	v_mov_b64_e32 v[98:99], 0
	v_mov_b64_e32 v[100:101], 0
	v_mov_b64_e32 v[102:103], 0
	v_mov_b64_e32 v[104:105], 0
	v_mov_b64_e32 v[106:107], 0
	v_mov_b64_e32 v[108:109], 0
	v_mov_b64_e32 v[110:111], 0
	v_mov_b64_e32 v[112:113], 0
	v_mov_b64_e32 v[114:115], 0
	v_mov_b64_e32 v[116:117], 0
	v_mov_b64_e32 v[118:119], 0
	v_mov_b64_e32 v[120:121], 0
	v_mov_b64_e32 v[122:123], 0
	v_mov_b64_e32 v[124:125], 0
	v_mov_b64_e32 v[126:127], 0

.LBB0_1414:
	s_ashr_i32 s51, s50, 31
	s_lshl_b64 s[52:53], s[50:51], 19
	s_add_u32 s52, s13, s52
	s_addc_u32 s53, s17, s53
	s_and_b64 s[54:55], s[2:3], exec
	s_cselect_b32 s51, s53, s57
	s_cselect_b32 s76, s52, s56
	s_ashr_i32 s45, s44, 31
	s_lshl_b64 s[54:55], s[44:45], 19
	s_add_u32 s54, s62, s54
	s_addc_u32 s55, s63, s55
	s_and_b64 s[60:61], s[2:3], exec
	s_cselect_b32 s45, s55, s59
	s_cselect_b32 s77, s54, s58
	s_add_u32 s56, s56, 0x40080
	s_addc_u32 s57, s57, 0
	s_add_u32 s78, s58, 0x100
	s_addc_u32 s79, s59, 0
	s_mov_b32 s80, -2
	v_mov_b64_e32 v[0:1], 0
	v_mov_b64_e32 v[2:3], 0
	v_mov_b64_e32 v[4:5], 0
	v_mov_b64_e32 v[6:7], 0
	v_mov_b64_e32 v[8:9], 0
	v_mov_b64_e32 v[10:11], 0
	v_mov_b64_e32 v[12:13], 0
	v_mov_b64_e32 v[14:15], 0
	v_mov_b64_e32 v[16:17], 0
	v_mov_b64_e32 v[18:19], 0
	v_mov_b64_e32 v[20:21], 0
	v_mov_b64_e32 v[22:23], 0
	v_mov_b64_e32 v[24:25], 0
	v_mov_b64_e32 v[26:27], 0
	v_mov_b64_e32 v[28:29], 0
	v_mov_b64_e32 v[30:31], 0
	v_mov_b64_e32 v[32:33], 0
	v_mov_b64_e32 v[34:35], 0
	v_mov_b64_e32 v[36:37], 0
	v_mov_b64_e32 v[38:39], 0
	v_mov_b64_e32 v[40:41], 0
	v_mov_b64_e32 v[42:43], 0
	v_mov_b64_e32 v[44:45], 0
	v_mov_b64_e32 v[46:47], 0
	v_mov_b64_e32 v[48:49], 0
	v_mov_b64_e32 v[50:51], 0
	v_mov_b64_e32 v[52:53], 0
	v_mov_b64_e32 v[54:55], 0
	v_mov_b64_e32 v[56:57], 0
	v_mov_b64_e32 v[58:59], 0
	v_mov_b64_e32 v[60:61], 0
	v_mov_b64_e32 v[62:63], 0
	v_mov_b64_e32 v[64:65], 0
	v_mov_b64_e32 v[66:67], 0
	v_mov_b64_e32 v[68:69], 0
	v_mov_b64_e32 v[70:71], 0
	v_mov_b64_e32 v[72:73], 0
	v_mov_b64_e32 v[74:75], 0
	v_mov_b64_e32 v[76:77], 0
	v_mov_b64_e32 v[78:79], 0
	v_mov_b64_e32 v[80:81], 0
	v_mov_b64_e32 v[82:83], 0
	v_mov_b64_e32 v[84:85], 0
	v_mov_b64_e32 v[86:87], 0
	v_mov_b64_e32 v[88:89], 0
	v_mov_b64_e32 v[90:91], 0
	v_mov_b64_e32 v[92:93], 0
	v_mov_b64_e32 v[94:95], 0
	v_mov_b64_e32 v[96:97], 0
	v_mov_b64_e32 v[98:99], 0
	v_mov_b64_e32 v[100:101], 0
	v_mov_b64_e32 v[102:103], 0
	v_mov_b64_e32 v[104:105], 0
	v_mov_b64_e32 v[106:107], 0
	v_mov_b64_e32 v[108:109], 0
	v_mov_b64_e32 v[110:111], 0
	v_mov_b64_e32 v[112:113], 0
	v_mov_b64_e32 v[114:115], 0
	v_mov_b64_e32 v[116:117], 0
	v_mov_b64_e32 v[118:119], 0
	v_mov_b64_e32 v[120:121], 0
	v_mov_b64_e32 v[122:123], 0
	v_mov_b64_e32 v[124:125], 0
	v_mov_b64_e32 v[126:127], 0
	s_waitcnt vmcnt(0)

.LBB0_1551:
	s_ashr_i32 s55, s54, 31
	s_lshl_b64 s[56:57], s[54:55], 19
	s_add_u32 s56, s17, s56
	s_addc_u32 s57, s66, s57
	s_and_b64 s[58:59], s[6:7], exec
	s_cselect_b32 s55, s57, s61
	s_cselect_b32 s84, s56, s60
	s_ashr_i32 s53, s52, 31
	s_lshl_b64 s[58:59], s[52:53], 19
	s_add_u32 s58, s67, s58
	s_addc_u32 s59, s68, s59
	s_and_b64 s[64:65], s[6:7], exec
	s_cselect_b32 s53, s59, s63
	s_cselect_b32 s85, s58, s62
	s_add_u32 s60, s60, 0x40080
	s_addc_u32 s61, s61, 0
	s_add_u32 s86, s62, 0x100
	s_addc_u32 s87, s63, 0
	s_mov_b32 s88, -2
	v_mov_b64_e32 v[0:1], 0
	v_mov_b64_e32 v[2:3], 0
	v_mov_b64_e32 v[4:5], 0
	v_mov_b64_e32 v[6:7], 0
	v_mov_b64_e32 v[8:9], 0
	v_mov_b64_e32 v[10:11], 0
	v_mov_b64_e32 v[12:13], 0
	v_mov_b64_e32 v[14:15], 0
	v_mov_b64_e32 v[16:17], 0
	v_mov_b64_e32 v[18:19], 0
	v_mov_b64_e32 v[20:21], 0
	v_mov_b64_e32 v[22:23], 0
	v_mov_b64_e32 v[24:25], 0
	v_mov_b64_e32 v[26:27], 0
	v_mov_b64_e32 v[28:29], 0
	v_mov_b64_e32 v[30:31], 0
	v_mov_b64_e32 v[32:33], 0
	v_mov_b64_e32 v[34:35], 0
	v_mov_b64_e32 v[36:37], 0
	v_mov_b64_e32 v[38:39], 0
	v_mov_b64_e32 v[40:41], 0
	v_mov_b64_e32 v[42:43], 0
	v_mov_b64_e32 v[44:45], 0
	v_mov_b64_e32 v[46:47], 0
	v_mov_b64_e32 v[48:49], 0
	v_mov_b64_e32 v[50:51], 0
	v_mov_b64_e32 v[52:53], 0
	v_mov_b64_e32 v[54:55], 0
	v_mov_b64_e32 v[56:57], 0
	v_mov_b64_e32 v[58:59], 0
	v_mov_b64_e32 v[60:61], 0
	v_mov_b64_e32 v[62:63], 0
	v_mov_b64_e32 v[96:97], 0
	v_mov_b64_e32 v[98:99], 0
	v_mov_b64_e32 v[100:101], 0
	v_mov_b64_e32 v[102:103], 0
	v_mov_b64_e32 v[104:105], 0
	v_mov_b64_e32 v[106:107], 0
	v_mov_b64_e32 v[108:109], 0
	v_mov_b64_e32 v[110:111], 0
	v_mov_b64_e32 v[112:113], 0
	v_mov_b64_e32 v[114:115], 0
	v_mov_b64_e32 v[116:117], 0
	v_mov_b64_e32 v[118:119], 0
	v_mov_b64_e32 v[120:121], 0
	v_mov_b64_e32 v[122:123], 0
	v_mov_b64_e32 v[124:125], 0
	v_mov_b64_e32 v[126:127], 0
	v_mov_b64_e32 v[128:129], 0
	v_mov_b64_e32 v[130:131], 0
	v_mov_b64_e32 v[132:133], 0
	v_mov_b64_e32 v[134:135], 0
	v_mov_b64_e32 v[136:137], 0
	v_mov_b64_e32 v[138:139], 0
	v_mov_b64_e32 v[140:141], 0
	v_mov_b64_e32 v[142:143], 0
	v_mov_b64_e32 v[144:145], 0
	v_mov_b64_e32 v[146:147], 0
	v_mov_b64_e32 v[148:149], 0
	v_mov_b64_e32 v[150:151], 0
	v_mov_b64_e32 v[152:153], 0
	v_mov_b64_e32 v[154:155], 0
	v_mov_b64_e32 v[156:157], 0
	v_mov_b64_e32 v[158:159], 0

.LBB0_1557:
	s_or_saveexec_b64 s[64:65], s[64:65]
	v_lshl_add_u32 v208, s0, 8, v169
	s_xor_b64 exec, exec, s[64:65]
	s_cbranch_execz .LBB0_1559
	v_mov_b32_e32 v214, v147
	s_waitcnt vmcnt(0)
	v_mov_b32_e32 v215, v95
	v_mov_b32_e32 v198, v91
	v_pk_mul_f32 v[198:199], v[214:215], v[198:199]
	s_nop 0
	v_fma_f32 v182, v83, v196, v199
	v_add_f32_e32 v182, v198, v182
	v_add_f32_e32 v182, v87, v182
	v_mov_b32_e32 v198, v146
	v_mov_b32_e32 v199, v94
	v_mov_b32_e32 v196, v90
	v_mul_f32_e32 v184, v182, v182
	v_pk_mul_f32 v[196:197], v[198:199], v[196:197]
	v_fmamk_f32 v184, v184, 0xbdd2d3e8, v206
	v_fma_f32 v186, v82, v194, v197
	v_mul_f32_e32 v184, v182, v184
	v_add_f32_e32 v186, v196, v186
	v_exp_f32_e32 v184, v184
	v_add_f32_e32 v186, v86, v186
	v_mul_f32_e32 v188, v186, v186
	v_fmamk_f32 v188, v188, 0xbdd2d3e8, v206
	v_mul_f32_e32 v188, v186, v188
	v_exp_f32_e32 v188, v188
	v_add_f32_e32 v184, 1.0, v184
	v_rcp_f32_e32 v184, v184
	v_mov_b32_e32 v196, v145
	v_add_f32_e32 v188, 1.0, v188
	v_mov_b32_e32 v197, v93
	v_mov_b32_e32 v194, v89
	v_rcp_f32_e32 v188, v188
	v_mul_f32_e32 v182, v182, v184
	v_pk_mul_f32 v[194:195], v[196:197], v[194:195]
	v_mul_f32_e32 v198, v159, v182
	v_fma_f32 v182, v81, v192, v195
	v_add_f32_e32 v182, v194, v182
	v_mov_b32_e32 v194, v144
	v_mov_b32_e32 v195, v92
	v_mov_b32_e32 v192, v88
	v_pk_mul_f32 v[192:193], v[194:195], v[192:193]
	v_mul_f32_e32 v159, v186, v188
	v_fma_f32 v186, v80, v213, v193
	v_add_f32_e32 v182, v85, v182
	v_add_f32_e32 v186, v192, v186
	v_mul_f32_e32 v184, v182, v182
	v_add_f32_e32 v186, v84, v186
	v_fmamk_f32 v184, v184, 0xbdd2d3e8, v206
	v_mul_f32_e32 v188, v186, v186
	v_mul_f32_e32 v184, v182, v184
	v_fmamk_f32 v188, v188, 0xbdd2d3e8, v206
	v_exp_f32_e32 v184, v184
	v_mul_f32_e32 v188, v186, v188
	v_exp_f32_e32 v188, v188
	v_mul_f32_e32 v192, v158, v159
	v_add_f32_e32 v158, 1.0, v184
	v_rcp_f32_e32 v184, v158
	v_add_f32_e32 v158, 1.0, v188
	v_rcp_f32_e32 v193, v158
	v_fma_f32 v158, v75, v151, v71
	v_fmac_f32_e32 v158, v79, v189
	v_fma_f32 v188, v67, v212, v158
	v_mul_f32_e32 v158, v188, v188
	v_fmamk_f32 v158, v158, 0xbdd2d3e8, v206
	v_mul_f32_e32 v158, v188, v158
	v_exp_f32_e32 v158, v158
	v_mul_f32_e32 v159, v182, v184
	v_mul_f32_e32 v189, v157, v159
	v_mul_f32_e32 v157, v186, v193
	v_add_f32_e32 v158, 1.0, v158
	v_rcp_f32_e32 v182, v158
	v_fma_f32 v158, v74, v150, v70
	v_fmac_f32_e32 v158, v78, v187
	v_mul_f32_e32 v186, v156, v157
	v_fma_f32 v158, v66, v211, v158
	v_mul_f32_e32 v159, v158, v158
	v_fmamk_f32 v159, v159, 0xbdd2d3e8, v206
	v_mul_f32_e32 v159, v158, v159
	v_exp_f32_e32 v159, v159
	v_mul_f32_e32 v156, v188, v182
	v_mul_f32_e32 v155, v155, v156
	v_add_f32_e32 v156, 1.0, v159
	v_rcp_f32_e32 v159, v156
	v_fma_f32 v156, v73, v149, v69
	v_fmac_f32_e32 v156, v77, v185
	v_fma_f32 v184, v65, v210, v156
	v_mul_f32_e32 v156, v184, v184
	v_fmamk_f32 v156, v156, 0xbdd2d3e8, v206
	v_mul_f32_e32 v156, v184, v156
	v_exp_f32_e32 v185, v156
	v_fma_f32 v156, v72, v148, v68
	v_fmac_f32_e32 v156, v76, v183
	v_mul_f32_e32 v158, v158, v159
	v_fma_f32 v156, v64, v209, v156
	v_mul_f32_e32 v157, v156, v156
	v_fmamk_f32 v157, v157, 0xbdd2d3e8, v206
	v_mul_f32_e32 v157, v156, v157
	v_exp_f32_e32 v157, v157
	v_add_f32_e32 v159, 1.0, v185
	v_rcp_f32_e32 v159, v159
	v_mul_f32_e32 v154, v154, v158
	v_add_f32_e32 v157, 1.0, v157
	v_rcp_f32_e32 v157, v157
	v_mul_f32_e32 v158, v184, v159
	v_mul_f32_e32 v153, v153, v158
	v_mov_b32_e32 v182, v73
	v_mul_f32_e32 v156, v156, v157
	v_mul_f32_e32 v152, v152, v156
	v_mov_b64_e32 v[156:157], s[10:11]
	v_mad_i64_i32 v[156:157], s[0:1], v208, s83, v[156:157]
	v_cvt_pk_bf16_f32 v152, v152, v153
	v_cvt_pk_bf16_f32 v153, v154, v155
	v_cvt_pk_bf16_f32 v154, v186, v189
	v_lshl_add_u64 v[156:157], v[180:181], 1, v[156:157]
	v_mov_b32_e32 v184, v75
	v_mov_b32_e32 v186, v89
	v_mov_b32_e32 v188, v91
	v_cvt_pk_bf16_f32 v155, v192, v198
	global_store_dwordx4 v[156:157], v[152:155], off

.LBB0_1563:
	s_andn2_saveexec_b64 s[62:63], s[62:63]
	s_cbranch_execz .LBB0_1565
	v_fma_f32 v104, v188, v51, v87
	v_fmac_f32_e32 v104, v95, v189
	v_fma_f32 v103, v83, v103, v104
	v_mul_f32_e32 v104, v103, v103
	v_fmamk_f32 v104, v104, 0xbdd2d3e8, v206
	v_mul_f32_e32 v104, v103, v104
	v_exp_f32_e32 v106, v104
	v_fma_f32 v104, v90, v50, v86
	v_fmac_f32_e32 v104, v94, v91
	v_fma_f32 v91, v82, v102, v104
	v_mul_f32_e32 v102, v91, v91
	v_fmamk_f32 v102, v102, 0xbdd2d3e8, v206
	v_mul_f32_e32 v102, v91, v102
	v_exp_f32_e32 v102, v102
	v_add_f32_e32 v104, 1.0, v106
	v_rcp_f32_e32 v104, v104
	v_add_f32_e32 v102, 1.0, v102
	v_rcp_f32_e32 v102, v102
	v_mul_f32_e32 v103, v103, v104
	v_mul_f32_e32 v104, v63, v103
	v_mul_f32_e32 v63, v91, v102
	v_fma_f32 v102, v186, v49, v85
	v_fmac_f32_e32 v102, v93, v187
	v_fma_f32 v91, v81, v101, v102
	v_fma_f32 v102, v88, v48, v84
	v_fmac_f32_e32 v102, v92, v89
	v_fma_f32 v89, v80, v100, v102
	v_mul_f32_e32 v101, v91, v91
	v_fmamk_f32 v101, v101, 0xbdd2d3e8, v206
	v_mul_f32_e32 v100, v89, v89
	v_mul_f32_e32 v101, v91, v101
	v_fmamk_f32 v100, v100, 0xbdd2d3e8, v206
	v_exp_f32_e32 v101, v101
	v_mul_f32_e32 v100, v89, v100
	v_exp_f32_e32 v100, v100
	v_mul_f32_e32 v102, v62, v63
	v_add_f32_e32 v62, 1.0, v101
	v_rcp_f32_e32 v101, v62
	v_add_f32_e32 v62, 1.0, v100
	v_rcp_f32_e32 v100, v62
	v_fma_f32 v62, v184, v55, v71
	v_fmac_f32_e32 v62, v79, v185
	v_fma_f32 v99, v67, v99, v62
	v_mul_f32_e32 v62, v99, v99
	v_fmamk_f32 v62, v62, 0xbdd2d3e8, v206
	v_mul_f32_e32 v62, v99, v62
	v_exp_f32_e32 v62, v62
	v_mul_f32_e32 v63, v91, v101
	v_mul_f32_e32 v91, v61, v63
	v_mul_f32_e32 v61, v89, v100
	v_add_f32_e32 v62, 1.0, v62
	v_rcp_f32_e32 v89, v62
	v_fma_f32 v62, v74, v54, v70
	v_fmac_f32_e32 v62, v78, v75
	v_mul_f32_e32 v75, v60, v61
	v_fma_f32 v62, v66, v98, v62
	v_mul_f32_e32 v63, v62, v62
	v_fmamk_f32 v63, v63, 0xbdd2d3e8, v206
	v_mul_f32_e32 v63, v62, v63
	v_exp_f32_e32 v63, v63
	v_mul_f32_e32 v60, v99, v89
	v_mul_f32_e32 v59, v59, v60
	v_add_f32_e32 v60, 1.0, v63
	v_rcp_f32_e32 v63, v60
	v_fma_f32 v60, v182, v53, v69
	v_fmac_f32_e32 v60, v77, v183
	v_mul_f32_e32 v62, v62, v63
	v_fma_f32 v89, v65, v97, v60
	v_mul_f32_e32 v60, v89, v89
	v_fmamk_f32 v60, v60, 0xbdd2d3e8, v206
	v_mul_f32_e32 v60, v89, v60
	v_exp_f32_e32 v97, v60
	v_fma_f32 v60, v72, v52, v68
	v_fmac_f32_e32 v60, v76, v73
	v_add_f32_e32 v63, 1.0, v97
	v_fma_f32 v60, v64, v96, v60
	v_mul_f32_e32 v61, v60, v60
	v_fmamk_f32 v61, v61, 0xbdd2d3e8, v206
	v_mul_f32_e32 v61, v60, v61
	v_exp_f32_e32 v61, v61
	v_rcp_f32_e32 v63, v63
	v_mul_f32_e32 v58, v58, v62
	v_add_f32_e32 v61, 1.0, v61
	v_rcp_f32_e32 v61, v61
	v_mul_f32_e32 v62, v89, v63
	v_mul_f32_e32 v57, v57, v62
	v_add_u32_e32 v62, 0x80, v208
	v_mul_f32_e32 v60, v60, v61
	v_mul_f32_e32 v56, v56, v60
	v_mov_b64_e32 v[60:61], s[10:11]
	v_mad_i64_i32 v[60:61], s[0:1], v62, s83, v[60:61]
	v_lshl_add_u64 v[60:61], v[180:181], 1, v[60:61]
	v_cvt_pk_bf16_f32 v56, v56, v57
	v_cvt_pk_bf16_f32 v57, v58, v59
	v_cvt_pk_bf16_f32 v58, v75, v91
	v_cvt_pk_bf16_f32 v59, v102, v104
	global_store_dwordx4 v[60:61], v[56:59], off

.LBB0_1703:
	s_add_u32 s44, s44, 0xb0080
	s_addc_u32 s45, s45, 0
	s_add_u32 s66, s46, 0x100
	s_addc_u32 s67, s47, 0
	s_mov_b32 s68, -2
	v_mov_b64_e32 v[0:1], 0
	v_mov_b64_e32 v[2:3], 0
	v_mov_b64_e32 v[4:5], 0
	v_mov_b64_e32 v[6:7], 0
	v_mov_b64_e32 v[8:9], 0
	v_mov_b64_e32 v[10:11], 0
	v_mov_b64_e32 v[12:13], 0
	v_mov_b64_e32 v[14:15], 0
	v_mov_b64_e32 v[16:17], 0
	v_mov_b64_e32 v[18:19], 0
	v_mov_b64_e32 v[20:21], 0
	v_mov_b64_e32 v[22:23], 0
	v_mov_b64_e32 v[24:25], 0
	v_mov_b64_e32 v[26:27], 0
	v_mov_b64_e32 v[28:29], 0
	v_mov_b64_e32 v[30:31], 0
	v_mov_b64_e32 v[32:33], 0
	v_mov_b64_e32 v[34:35], 0
	v_mov_b64_e32 v[36:37], 0
	v_mov_b64_e32 v[38:39], 0
	v_mov_b64_e32 v[40:41], 0
	v_mov_b64_e32 v[42:43], 0
	v_mov_b64_e32 v[44:45], 0
	v_mov_b64_e32 v[46:47], 0
	v_mov_b64_e32 v[48:49], 0
	v_mov_b64_e32 v[50:51], 0
	v_mov_b64_e32 v[52:53], 0
	v_mov_b64_e32 v[54:55], 0
	v_mov_b64_e32 v[56:57], 0
	v_mov_b64_e32 v[58:59], 0
	v_mov_b64_e32 v[60:61], 0
	v_mov_b64_e32 v[62:63], 0
	v_mov_b64_e32 v[64:65], 0
	v_mov_b64_e32 v[66:67], 0
	v_mov_b64_e32 v[68:69], 0
	v_mov_b64_e32 v[70:71], 0
	v_mov_b64_e32 v[72:73], 0
	v_mov_b64_e32 v[74:75], 0
	v_mov_b64_e32 v[76:77], 0
	v_mov_b64_e32 v[78:79], 0
	v_mov_b64_e32 v[80:81], 0
	v_mov_b64_e32 v[82:83], 0
	v_mov_b64_e32 v[84:85], 0
	v_mov_b64_e32 v[86:87], 0
	v_mov_b64_e32 v[88:89], 0
	v_mov_b64_e32 v[90:91], 0
	v_mov_b64_e32 v[92:93], 0
	v_mov_b64_e32 v[94:95], 0
	v_mov_b64_e32 v[96:97], 0
	v_mov_b64_e32 v[98:99], 0
	v_mov_b64_e32 v[100:101], 0
	v_mov_b64_e32 v[102:103], 0
	v_mov_b64_e32 v[104:105], 0
	v_mov_b64_e32 v[106:107], 0
	v_mov_b64_e32 v[108:109], 0
	v_mov_b64_e32 v[110:111], 0
	v_mov_b64_e32 v[112:113], 0
	v_mov_b64_e32 v[114:115], 0
	v_mov_b64_e32 v[116:117], 0
	v_mov_b64_e32 v[118:119], 0
	v_mov_b64_e32 v[120:121], 0
	v_mov_b64_e32 v[122:123], 0
	v_mov_b64_e32 v[124:125], 0
	v_mov_b64_e32 v[126:127], 0
	s_waitcnt vmcnt(0)
